# P0 rmsnorm: norm_g hoisted out of the loop (15 reload+vmcnt(0) pairs per iteration removed); hg_unit_c initial block: G rows loaded straight into final registers, six mid-block waits removed
# speedup vs baseline: 1.1087x; 1.0007x over previous
; __device__ __forceinline__ unsigned pk2(float lo, float hi) { return f2bf(lo) | (f2bf(hi) << 16); }
; __global__ void __launch_bounds__(512, 2) mk_fwd(Args args) {
;     ...
;         for (int m4 = gw * 4; m4 < M_TOK; m4 += NGW * 4) {
;             f32x4 v[4][4]; float s2[4];
; #pragma unroll
;             for (int q = 0; q < 4; ++q) { const f32x4* xr = (const f32x4*)(x + (size_t)(m4 + q) * 1024) + lane;
; #pragma unroll
;                 for (int j = 0; j < 4; ++j) v[q][j] = xr[64 * j]; }
; #pragma unroll
;             for (int q = 0; q < 4; ++q) { s2[q] = 0.f;
; #pragma unroll
;                 for (int j = 0; j < 4; ++j) s2[q] += (v[q][j][0] * v[q][j][0] + v[q][j][1] * v[q][j][1]) + (v[q][j][2] * v[q][j][2] + v[q][j][3] * v[q][j][3]); }
; #pragma unroll
;             for (int o = 1; o < 64; o <<= 1) {
; #pragma unroll
;                 for (int q = 0; q < 4; ++q) s2[q] += __shfl_xor(s2[q], o); }
; #pragma unroll
;             for (int q = 0; q < 4; ++q) {
;                 const float rstd = __builtin_amdgcn_rsqf(s2[q] * (1.f / 1024.f) + RMS_EPS);
;                 u32x2* o8 = (u32x2*)(Hn + (size_t)(m4 + q) * 1024) + lane;
; #pragma unroll
;                 for (int j = 0; j < 4; ++j) { const f32x4 gg = *((const f32x4*)norm_g + lane + 64 * j);
;                     o8[64 * j] = (u32x2){pk2(v[q][j][0] * rstd * gg[0], v[q][j][1] * rstd * gg[1]), pk2(v[q][j][2] * rstd * gg[2], v[q][j][3] * rstd * gg[3])}; }
;             }
.LBB0_10:
	s_or_b64 exec, exec, s[4:5]
	s_movk_i32 s0, 0x1000
	v_cmp_gt_i32_e32 vcc, s0, v169
	s_and_saveexec_b64 s[8:9], vcc
	s_cbranch_execz .LBB0_13
	v_mbcnt_lo_u32_b32 v0, -1, 0
	v_mbcnt_hi_u32_b32 v2, -1, v0
	v_and_b32_e32 v0, 64, v2
	v_readlane_b32 s16, v250, 1
	v_add_u32_e32 v3, 64, v0
	v_lshlrev_b32_e32 v0, 4, v170
	v_mov_b32_e32 v1, 0
	v_readlane_b32 s18, v250, 3
	v_readlane_b32 s19, v250, 4
	v_lshlrev_b32_e32 v68, 2, v169
	v_ashrrev_i32_e32 v69, 31, v68
	v_lshl_add_u64 v[70:71], s[18:19], 0, v[0:1]
	v_xor_b32_e32 v1, 1, v2
	v_cmp_lt_i32_e32 vcc, v1, v3
	s_mov_b64 s[4:5], 0x1c00000
	s_lshl_b32 s10, s70, 5
	v_cndmask_b32_e32 v1, v2, v1, vcc
	v_lshlrev_b32_e32 v92, 2, v1
	v_xor_b32_e32 v1, 2, v2
	v_cmp_lt_i32_e32 vcc, v1, v3
	v_readlane_b32 s17, v250, 2
	s_ashr_i32 s11, s10, 31
	v_cndmask_b32_e32 v1, v2, v1, vcc
	v_lshlrev_b32_e32 v93, 2, v1
	v_xor_b32_e32 v1, 4, v2
	v_cmp_lt_i32_e32 vcc, v1, v3
	s_lshl_b64 s[12:13], s[10:11], 11
	s_lshl_b64 s[14:15], s[10:11], 12
	v_cndmask_b32_e32 v1, v2, v1, vcc
	v_lshlrev_b32_e32 v94, 2, v1
	v_xor_b32_e32 v1, 8, v2
	v_cmp_lt_i32_e32 vcc, v1, v3
	s_movk_i32 s1, 0x7fff
	s_movk_i32 s11, 0x3fff
	v_cndmask_b32_e32 v1, v2, v1, vcc
	v_lshlrev_b32_e32 v95, 2, v1
	v_xor_b32_e32 v1, 16, v2
	v_cmp_lt_i32_e32 vcc, v1, v3
	v_mov_b32_e32 v98, 1
	v_readlane_b32 s20, v250, 5
	v_cndmask_b32_e32 v1, v2, v1, vcc
	v_lshlrev_b32_e32 v96, 2, v1
	v_xor_b32_e32 v1, 32, v2
	v_cmp_lt_i32_e32 vcc, v1, v3
	v_readlane_b32 s21, v250, 6
	v_readlane_b32 s22, v250, 7
	v_cndmask_b32_e32 v1, v2, v1, vcc
	v_lshlrev_b64 v[2:3], 11, v[68:69]
	v_lshl_or_b32 v2, v170, 3, v2
	v_lshl_add_u64 v[2:3], s[66:67], 0, v[2:3]
	v_lshl_add_u64 v[72:73], v[2:3], 0, s[4:5]
	v_lshlrev_b64 v[2:3], 12, v[68:69]
	v_or_b32_e32 v2, v2, v0
	v_lshlrev_b32_e32 v97, 2, v1
	v_lshl_add_u64 v[74:75], s[16:17], 0, v[2:3]
	s_mov_b64 s[16:17], 0
	v_mov_b32_e32 v69, 0x358637bd
	v_readlane_b32 s23, v250, 8
	v_readlane_b32 s24, v250, 9
	v_readlane_b32 s25, v250, 10
	v_readlane_b32 s26, v250, 11
	v_readlane_b32 s27, v250, 12
	v_readlane_b32 s28, v250, 13
	v_readlane_b32 s29, v250, 14
	v_readlane_b32 s30, v250, 15
	global_load_dwordx4 v[224:227], v[70:71], off
	global_load_dwordx4 v[228:231], v[70:71], off offset:1024
	global_load_dwordx4 v[232:235], v[70:71], off offset:2048
	global_load_dwordx4 v[236:239], v[70:71], off offset:3072
	v_readlane_b32 s31, v250, 16
	s_mov_b64 s[100:101], s[16:17]
	v_readfirstlane_b32 s98, v200
	s_nop 0
	s_lshr_b32 s98, s98, 6
	s_cmp_eq_u32 s98, 0
	s_cbranch_scc1 .Ldry_p0b_real
	s_mov_b64 exec, 0
	s_cmp_eq_u32 s98, 1
	s_cbranch_scc1 .Ldry_p0b_c1
	s_cmp_eq_u32 s98, 2
	s_cbranch_scc1 .Ldry_p0b_c2
	s_cmp_eq_u32 s98, 3
	s_cbranch_scc1 .Ldry_p0b_c3
	s_cmp_eq_u32 s98, 4
	s_cbranch_scc1 .Ldry_p0b_c4
	s_cmp_eq_u32 s98, 5
	s_cbranch_scc1 .Ldry_p0b_c5
	s_cmp_eq_u32 s98, 6
	s_cbranch_scc1 .Ldry_p0b_c6
	s_branch .Ldry_p0b_c7

; __device__ __forceinline__ unsigned pk2(float lo, float hi) { return f2bf(lo) | (f2bf(hi) << 16); }
; __global__ void __launch_bounds__(512, 2) mk_fwd(Args args) {
;     ...
;             for (int q = 0; q < 4; ++q) {
;                 const float rstd = __builtin_amdgcn_rsqf(s2[q] * (1.f / 1024.f) + RMS_EPS);
;                 u32x2* o8 = (u32x2*)(Hn + (size_t)(m4 + q) * 1024) + lane;
; #pragma unroll
;                 for (int j = 0; j < 4; ++j) { const f32x4 gg = *((const f32x4*)norm_g + lane + 64 * j);
;                     o8[64 * j] = (u32x2){pk2(v[q][j][0] * rstd * gg[0], v[q][j][1] * rstd * gg[1]), pk2(v[q][j][2] * rstd * gg[2], v[q][j][3] * rstd * gg[3])}; }
;             }
.Ldry_p0b_c3:
	v_pk_mul_f32 v[78:79], v[48:49], v[90:91] op_sel_hi:[0,1]
	v_add3_u32 v48, v18, v49, s1
	v_add3_u32 v49, v7, v84, s1
	v_add3_u32 v84, v6, v85, s1
	v_add3_u32 v42, v19, v42, s1
	v_pk_mul_f32 v[6:7], v[40:41], v[50:51] op_sel_hi:[0,1]
	v_and_b32_e32 v49, 0xffff0000, v49
	v_and_b32_e32 v50, 0xffff0000, v84
	v_or_b32_sdwa v49, v49, v42 dst_sel:DWORD dst_unused:UNUSED_PAD src0_sel:DWORD src1_sel:WORD_1
	v_or_b32_sdwa v48, v50, v48 dst_sel:DWORD dst_unused:UNUSED_PAD src0_sel:DWORD src1_sel:WORD_1
	global_store_dwordx2 v[72:73], v[48:49], off
	v_mov_b64_e32 v[48:49], v[228:229]
	v_pk_mul_f32 v[18:19], v[40:41], v[122:123] op_sel_hi:[0,1]
	v_mov_b32_e32 v8, v44
	v_mov_b32_e32 v9, v46
	v_mov_b32_e32 v46, v45
	v_mov_b32_e32 v0, v36
	v_mov_b32_e32 v1, v38
	v_mov_b32_e32 v38, v37
	s_waitcnt vmcnt(4)
	v_pk_mul_f32 v[44:45], v[34:35], v[34:35]
	v_pk_mul_f32 v[12:13], v[32:33], v[32:33]
	s_waitcnt vmcnt(3)
	v_pk_mul_f32 v[16:17], v[30:31], v[30:31]
	v_pk_mul_f32 v[36:37], v[28:29], v[28:29]
	s_waitcnt vmcnt(1)
	v_mul_f32_e32 v99, v20, v20
	v_pk_mul_f32 v[0:1], v[40:41], v[0:1] op_sel_hi:[0,1]
	v_mov_b64_e32 v[50:51], v[230:231]
	v_mov_b32_e32 v85, v50
	v_mov_b32_e32 v50, v49
	v_mov_b32_e32 v84, v48
	v_pk_mul_f32 v[10:11], v[50:51], v[10:11]
	v_pk_mul_f32 v[48:49], v[84:85], v[64:65]
	v_and_b32_sdwa v51, v11, v98 dst_sel:DWORD dst_unused:UNUSED_PAD src0_sel:WORD_1 src1_sel:DWORD
	v_and_b32_sdwa v64, v10, v98 dst_sel:DWORD dst_unused:UNUSED_PAD src0_sel:WORD_1 src1_sel:DWORD
	v_and_b32_sdwa v42, v49, v98 dst_sel:DWORD dst_unused:UNUSED_PAD src0_sel:WORD_1 src1_sel:DWORD
	v_and_b32_sdwa v50, v48, v98 dst_sel:DWORD dst_unused:UNUSED_PAD src0_sel:WORD_1 src1_sel:DWORD
	v_add3_u32 v11, v11, v51, s1
	v_add3_u32 v10, v10, v64, s1
	v_add3_u32 v48, v48, v50, s1
	v_add3_u32 v42, v49, v42, s1
	v_and_b32_e32 v11, 0xffff0000, v11
	v_and_b32_e32 v10, 0xffff0000, v10
	v_or_b32_sdwa v11, v11, v42 dst_sel:DWORD dst_unused:UNUSED_PAD src0_sel:DWORD src1_sel:WORD_1
	v_or_b32_sdwa v10, v10, v48 dst_sel:DWORD dst_unused:UNUSED_PAD src0_sel:DWORD src1_sel:WORD_1
	global_store_dwordx2 v[72:73], v[10:11], off offset:512
	v_mov_b64_e32 v[48:49], v[232:233]
	v_mov_b64_e32 v[50:51], v[234:235]
	v_mov_b32_e32 v11, v50
	v_mov_b32_e32 v50, v49
	v_mov_b32_e32 v10, v48
	v_pk_mul_f32 v[14:15], v[50:51], v[14:15]
	v_pk_mul_f32 v[10:11], v[10:11], v[80:81]
	v_and_b32_sdwa v49, v15, v98 dst_sel:DWORD dst_unused:UNUSED_PAD src0_sel:WORD_1 src1_sel:DWORD
	v_and_b32_sdwa v50, v14, v98 dst_sel:DWORD dst_unused:UNUSED_PAD src0_sel:WORD_1 src1_sel:DWORD
	v_and_b32_sdwa v42, v11, v98 dst_sel:DWORD dst_unused:UNUSED_PAD src0_sel:WORD_1 src1_sel:DWORD
	v_and_b32_sdwa v48, v10, v98 dst_sel:DWORD dst_unused:UNUSED_PAD src0_sel:WORD_1 src1_sel:DWORD
	v_add3_u32 v15, v15, v49, s1
	v_add3_u32 v14, v14, v50, s1
	v_add3_u32 v10, v10, v48, s1
	v_add3_u32 v11, v11, v42, s1
	v_and_b32_e32 v15, 0xffff0000, v15
	v_and_b32_e32 v14, 0xffff0000, v14
	v_or_b32_sdwa v11, v15, v11 dst_sel:DWORD dst_unused:UNUSED_PAD src0_sel:DWORD src1_sel:WORD_1
	v_or_b32_sdwa v10, v14, v10 dst_sel:DWORD dst_unused:UNUSED_PAD src0_sel:DWORD src1_sel:WORD_1
	global_store_dwordx2 v[72:73], v[10:11], off offset:1024
	v_mov_b64_e32 v[48:49], v[236:237]
	v_mov_b64_e32 v[50:51], v[238:239]
	v_mov_b32_e32 v11, v50
	v_mov_b32_e32 v50, v49
	v_mov_b32_e32 v10, v48
	v_pk_mul_f32 v[2:3], v[50:51], v[2:3]
	v_pk_mul_f32 v[10:11], v[10:11], v[82:83]
	v_and_b32_sdwa v42, v3, v98 dst_sel:DWORD dst_unused:UNUSED_PAD src0_sel:WORD_1 src1_sel:DWORD
	v_and_b32_sdwa v48, v2, v98 dst_sel:DWORD dst_unused:UNUSED_PAD src0_sel:WORD_1 src1_sel:DWORD
	v_and_b32_sdwa v14, v11, v98 dst_sel:DWORD dst_unused:UNUSED_PAD src0_sel:WORD_1 src1_sel:DWORD
	v_and_b32_sdwa v15, v10, v98 dst_sel:DWORD dst_unused:UNUSED_PAD src0_sel:WORD_1 src1_sel:DWORD
	v_add3_u32 v3, v3, v42, s1
	s_cbranch_execz .Ldry_p0b_real
.Ldry_p0b_c4:
	v_add3_u32 v2, v2, v48, s1
	v_add3_u32 v10, v10, v15, s1
	v_add3_u32 v11, v11, v14, s1
	v_and_b32_e32 v3, 0xffff0000, v3
	v_and_b32_e32 v2, 0xffff0000, v2
	v_or_b32_sdwa v3, v3, v11 dst_sel:DWORD dst_unused:UNUSED_PAD src0_sel:DWORD src1_sel:WORD_1
	v_or_b32_sdwa v2, v2, v10 dst_sel:DWORD dst_unused:UNUSED_PAD src0_sel:DWORD src1_sel:WORD_1
	global_store_dwordx2 v[72:73], v[2:3], off offset:1536
	v_mov_b64_e32 v[48:49], v[224:225]
	v_mov_b64_e32 v[50:51], v[226:227]
	v_mov_b32_e32 v3, v50
	v_mov_b32_e32 v50, v49
	v_mov_b32_e32 v2, v48
	v_pk_mul_f32 v[10:11], v[50:51], v[52:53]
	v_pk_mul_f32 v[2:3], v[2:3], v[66:67]
	v_and_b32_sdwa v42, v11, v98 dst_sel:DWORD dst_unused:UNUSED_PAD src0_sel:WORD_1 src1_sel:DWORD
	v_and_b32_sdwa v48, v10, v98 dst_sel:DWORD dst_unused:UNUSED_PAD src0_sel:WORD_1 src1_sel:DWORD
	v_and_b32_sdwa v14, v3, v98 dst_sel:DWORD dst_unused:UNUSED_PAD src0_sel:WORD_1 src1_sel:DWORD
	v_and_b32_sdwa v15, v2, v98 dst_sel:DWORD dst_unused:UNUSED_PAD src0_sel:WORD_1 src1_sel:DWORD
	v_add3_u32 v11, v11, v42, s1
	v_add3_u32 v10, v10, v48, s1
	v_add3_u32 v2, v2, v15, s1
	v_add3_u32 v3, v3, v14, s1
	v_and_b32_e32 v11, 0xffff0000, v11
	v_and_b32_e32 v10, 0xffff0000, v10
	v_or_b32_sdwa v3, v11, v3 dst_sel:DWORD dst_unused:UNUSED_PAD src0_sel:DWORD src1_sel:WORD_1
	v_or_b32_sdwa v2, v10, v2 dst_sel:DWORD dst_unused:UNUSED_PAD src0_sel:DWORD src1_sel:WORD_1
	global_store_dwordx2 v[72:73], v[2:3], off offset:2048
	v_mov_b64_e32 v[48:49], v[228:229]
	v_mov_b64_e32 v[50:51], v[230:231]
	v_mov_b32_e32 v3, v50
	v_mov_b32_e32 v50, v49
	v_mov_b32_e32 v2, v48
	v_pk_mul_f32 v[10:11], v[50:51], v[58:59]
	v_pk_mul_f32 v[2:3], v[2:3], v[56:57]
	v_and_b32_sdwa v42, v11, v98 dst_sel:DWORD dst_unused:UNUSED_PAD src0_sel:WORD_1 src1_sel:DWORD
; __device__ __forceinline__ unsigned pk2(float lo, float hi) { return f2bf(lo) | (f2bf(hi) << 16); }
; __global__ void __launch_bounds__(512, 2) mk_fwd(Args args) {
;     ...
;             for (int q = 0; q < 4; ++q) {
;                 const float rstd = __builtin_amdgcn_rsqf(s2[q] * (1.f / 1024.f) + RMS_EPS);
;                 u32x2* o8 = (u32x2*)(Hn + (size_t)(m4 + q) * 1024) + lane;
; #pragma unroll
;                 for (int j = 0; j < 4; ++j) { const f32x4 gg = *((const f32x4*)norm_g + lane + 64 * j);
;                     o8[64 * j] = (u32x2){pk2(v[q][j][0] * rstd * gg[0], v[q][j][1] * rstd * gg[1]), pk2(v[q][j][2] * rstd * gg[2], v[q][j][3] * rstd * gg[3])}; }
;             }
	v_and_b32_sdwa v48, v10, v98 dst_sel:DWORD dst_unused:UNUSED_PAD src0_sel:WORD_1 src1_sel:DWORD
	v_and_b32_sdwa v14, v3, v98 dst_sel:DWORD dst_unused:UNUSED_PAD src0_sel:WORD_1 src1_sel:DWORD
	v_and_b32_sdwa v15, v2, v98 dst_sel:DWORD dst_unused:UNUSED_PAD src0_sel:WORD_1 src1_sel:DWORD
	v_add3_u32 v11, v11, v42, s1
	v_add3_u32 v10, v10, v48, s1
	v_add3_u32 v2, v2, v15, s1
	v_add3_u32 v3, v3, v14, s1
	v_and_b32_e32 v11, 0xffff0000, v11
	v_and_b32_e32 v10, 0xffff0000, v10
	v_or_b32_sdwa v3, v11, v3 dst_sel:DWORD dst_unused:UNUSED_PAD src0_sel:DWORD src1_sel:WORD_1
	v_or_b32_sdwa v2, v10, v2 dst_sel:DWORD dst_unused:UNUSED_PAD src0_sel:DWORD src1_sel:WORD_1
	global_store_dwordx2 v[72:73], v[2:3], off offset:2560
	v_mov_b64_e32 v[48:49], v[232:233]
	v_mov_b64_e32 v[50:51], v[234:235]
	v_mov_b32_e32 v3, v50
	v_mov_b32_e32 v50, v49
	v_mov_b32_e32 v2, v48
	v_pk_mul_f32 v[10:11], v[50:51], v[62:63]
	v_pk_mul_f32 v[2:3], v[2:3], v[60:61]
	v_and_b32_sdwa v42, v11, v98 dst_sel:DWORD dst_unused:UNUSED_PAD src0_sel:WORD_1 src1_sel:DWORD
	v_and_b32_sdwa v48, v10, v98 dst_sel:DWORD dst_unused:UNUSED_PAD src0_sel:WORD_1 src1_sel:DWORD
	v_and_b32_sdwa v14, v3, v98 dst_sel:DWORD dst_unused:UNUSED_PAD src0_sel:WORD_1 src1_sel:DWORD
	v_and_b32_sdwa v15, v2, v98 dst_sel:DWORD dst_unused:UNUSED_PAD src0_sel:WORD_1 src1_sel:DWORD
	v_add3_u32 v11, v11, v42, s1
	v_add3_u32 v10, v10, v48, s1
	v_add3_u32 v2, v2, v15, s1
	v_add3_u32 v3, v3, v14, s1
	v_and_b32_e32 v11, 0xffff0000, v11
	v_and_b32_e32 v10, 0xffff0000, v10
	v_or_b32_sdwa v3, v11, v3 dst_sel:DWORD dst_unused:UNUSED_PAD src0_sel:DWORD src1_sel:WORD_1
	v_or_b32_sdwa v2, v10, v2 dst_sel:DWORD dst_unused:UNUSED_PAD src0_sel:DWORD src1_sel:WORD_1
	global_store_dwordx2 v[72:73], v[2:3], off offset:3072
	v_mov_b64_e32 v[48:49], v[236:237]
	v_mov_b64_e32 v[50:51], v[238:239]
	v_mov_b32_e32 v3, v50
	v_mov_b32_e32 v50, v49
	v_mov_b32_e32 v2, v48
	v_pk_mul_f32 v[10:11], v[50:51], v[54:55]
	v_pk_mul_f32 v[2:3], v[2:3], v[78:79]
	v_and_b32_sdwa v42, v11, v98 dst_sel:DWORD dst_unused:UNUSED_PAD src0_sel:WORD_1 src1_sel:DWORD
	v_and_b32_sdwa v48, v10, v98 dst_sel:DWORD dst_unused:UNUSED_PAD src0_sel:WORD_1 src1_sel:DWORD
	v_and_b32_sdwa v14, v3, v98 dst_sel:DWORD dst_unused:UNUSED_PAD src0_sel:WORD_1 src1_sel:DWORD
	v_and_b32_sdwa v15, v2, v98 dst_sel:DWORD dst_unused:UNUSED_PAD src0_sel:WORD_1 src1_sel:DWORD
	v_add3_u32 v11, v11, v42, s1
	s_cbranch_execz .Ldry_p0b_real
.Ldry_p0b_c5:
	v_add3_u32 v10, v10, v48, s1
	v_add3_u32 v2, v2, v15, s1
	v_add3_u32 v3, v3, v14, s1
	v_and_b32_e32 v11, 0xffff0000, v11
	v_and_b32_e32 v10, 0xffff0000, v10
	v_or_b32_sdwa v3, v11, v3 dst_sel:DWORD dst_unused:UNUSED_PAD src0_sel:DWORD src1_sel:WORD_1
	v_or_b32_sdwa v2, v10, v2 dst_sel:DWORD dst_unused:UNUSED_PAD src0_sel:DWORD src1_sel:WORD_1
	global_store_dwordx2 v[72:73], v[2:3], off offset:3584
	v_mov_b64_e32 v[48:49], v[224:225]
	v_mov_b32_e32 v42, v41
	v_lshl_add_u64 v[72:73], v[72:73], 0, s[12:13]
	v_mov_b64_e32 v[50:51], v[226:227]
	v_mov_b32_e32 v3, v50
	v_mov_b32_e32 v50, v49
	v_mov_b32_e32 v2, v48
	v_pk_mul_f32 v[6:7], v[50:51], v[6:7]
	v_pk_mul_f32 v[2:3], v[2:3], v[18:19]
	v_and_b32_sdwa v14, v7, v98 dst_sel:DWORD dst_unused:UNUSED_PAD src0_sel:WORD_1 src1_sel:DWORD
	v_and_b32_sdwa v15, v6, v98 dst_sel:DWORD dst_unused:UNUSED_PAD src0_sel:WORD_1 src1_sel:DWORD
	v_and_b32_sdwa v10, v3, v98 dst_sel:DWORD dst_unused:UNUSED_PAD src0_sel:WORD_1 src1_sel:DWORD
	v_and_b32_sdwa v11, v2, v98 dst_sel:DWORD dst_unused:UNUSED_PAD src0_sel:WORD_1 src1_sel:DWORD
	v_add3_u32 v7, v7, v14, s1
	v_add3_u32 v6, v6, v15, s1
	v_add3_u32 v2, v2, v11, s1
	v_add3_u32 v3, v3, v10, s1
	v_and_b32_e32 v7, 0xffff0000, v7
	v_and_b32_e32 v6, 0xffff0000, v6
	v_or_b32_sdwa v3, v7, v3 dst_sel:DWORD dst_unused:UNUSED_PAD src0_sel:DWORD src1_sel:WORD_1
	v_or_b32_sdwa v2, v6, v2 dst_sel:DWORD dst_unused:UNUSED_PAD src0_sel:DWORD src1_sel:WORD_1
	global_store_dwordx2 v[76:77], v[2:3], off
	v_mov_b64_e32 v[48:49], v[228:229]
	v_pk_mul_f32 v[2:3], v[40:41], v[8:9] op_sel_hi:[0,1]
	v_pk_mul_f32 v[6:7], v[40:41], v[46:47] op_sel_hi:[0,1]
	v_mov_b32_e32 v18, v32
	v_mov_b32_e32 v19, v34
	v_mov_b32_e32 v34, v33
	v_pk_mov_b32 v[32:33], v[12:13], v[44:45] op_sel:[1,0]
	v_mov_b32_e32 v13, v45
	v_mul_f32_e32 v15, v21, v21
	v_mul_f32_e32 v14, v27, v27
	v_pk_add_f32 v[12:13], v[32:33], v[12:13]
	v_mul_f32_e32 v46, v22, v22
	v_mul_f32_e32 v47, v23, v23
	v_pk_add_f32 v[12:13], v[12:13], v[12:13] op_sel:[0,1] op_sel_hi:[1,0]
	v_mov_b64_e32 v[50:51], v[230:231]
	v_mov_b32_e32 v9, v50
	v_mov_b32_e32 v50, v49
	v_mov_b32_e32 v8, v48
	v_pk_mul_f32 v[6:7], v[50:51], v[6:7]
	v_pk_mul_f32 v[2:3], v[8:9], v[2:3]
	v_and_b32_sdwa v10, v7, v98 dst_sel:DWORD dst_unused:UNUSED_PAD src0_sel:WORD_1 src1_sel:DWORD
	v_and_b32_sdwa v11, v6, v98 dst_sel:DWORD dst_unused:UNUSED_PAD src0_sel:WORD_1 src1_sel:DWORD
	v_and_b32_sdwa v8, v3, v98 dst_sel:DWORD dst_unused:UNUSED_PAD src0_sel:WORD_1 src1_sel:DWORD
	v_and_b32_sdwa v9, v2, v98 dst_sel:DWORD dst_unused:UNUSED_PAD src0_sel:WORD_1 src1_sel:DWORD
	v_add3_u32 v7, v7, v10, s1
	v_add3_u32 v6, v6, v11, s1
	v_add3_u32 v2, v2, v9, s1
	v_add3_u32 v3, v3, v8, s1
	v_and_b32_e32 v7, 0xffff0000, v7
	v_and_b32_e32 v6, 0xffff0000, v6
	v_or_b32_sdwa v3, v7, v3 dst_sel:DWORD dst_unused:UNUSED_PAD src0_sel:DWORD src1_sel:WORD_1
	v_or_b32_sdwa v2, v6, v2 dst_sel:DWORD dst_unused:UNUSED_PAD src0_sel:DWORD src1_sel:WORD_1
	global_store_dwordx2 v[76:77], v[2:3], off offset:512
	v_mov_b64_e32 v[6:7], v[232:233]
	v_pk_mul_f32 v[2:3], v[40:41], v[4:5] op_sel_hi:[0,1]
	v_pk_mul_f32 v[4:5], v[40:41], v[42:43] op_sel_hi:[0,1]
	v_mul_f32_e32 v10, v25, v25
	v_mov_b32_e32 v13, v99
	v_mov_b64_e32 v[8:9], v[234:235]
	v_mov_b32_e32 v43, v8
	v_mov_b32_e32 v8, v7
	v_mov_b32_e32 v42, v6
	v_pk_mul_f32 v[4:5], v[8:9], v[4:5]
	v_pk_mul_f32 v[2:3], v[42:43], v[2:3]
	v_and_b32_sdwa v8, v5, v98 dst_sel:DWORD dst_unused:UNUSED_PAD src0_sel:WORD_1 src1_sel:DWORD
	v_and_b32_sdwa v9, v4, v98 dst_sel:DWORD dst_unused:UNUSED_PAD src0_sel:WORD_1 src1_sel:DWORD
	v_and_b32_sdwa v6, v3, v98 dst_sel:DWORD dst_unused:UNUSED_PAD src0_sel:WORD_1 src1_sel:DWORD
	v_and_b32_sdwa v7, v2, v98 dst_sel:DWORD dst_unused:UNUSED_PAD src0_sel:WORD_1 src1_sel:DWORD
	v_add3_u32 v5, v5, v8, s1
	v_add3_u32 v4, v4, v9, s1
	s_cbranch_execz .Ldry_p0b_real
; __device__ __forceinline__ unsigned pk2(float lo, float hi) { return f2bf(lo) | (f2bf(hi) << 16); }
; __global__ void __launch_bounds__(512, 2) mk_fwd(Args args) {
;     ...
; #pragma unroll
;             for (int q = 0; q < 4; ++q) { s2[q] = 0.f;
; #pragma unroll
;                 for (int j = 0; j < 4; ++j) s2[q] += (v[q][j][0] * v[q][j][0] + v[q][j][1] * v[q][j][1]) + (v[q][j][2] * v[q][j][2] + v[q][j][3] * v[q][j][3]); }
; #pragma unroll
;             for (int o = 1; o < 64; o <<= 1) {
; #pragma unroll
;                 for (int q = 0; q < 4; ++q) s2[q] += __shfl_xor(s2[q], o); }
; #pragma unroll
;             for (int q = 0; q < 4; ++q) {
;                 const float rstd = __builtin_amdgcn_rsqf(s2[q] * (1.f / 1024.f) + RMS_EPS);
;                 u32x2* o8 = (u32x2*)(Hn + (size_t)(m4 + q) * 1024) + lane;
; #pragma unroll
;                 for (int j = 0; j < 4; ++j) { const f32x4 gg = *((const f32x4*)norm_g + lane + 64 * j);
;                     o8[64 * j] = (u32x2){pk2(v[q][j][0] * rstd * gg[0], v[q][j][1] * rstd * gg[1]), pk2(v[q][j][2] * rstd * gg[2], v[q][j][3] * rstd * gg[3])}; }
;             }
.Ldry_p0b_c6:
	v_add3_u32 v2, v2, v7, s1
	v_add3_u32 v3, v3, v6, s1
	v_and_b32_e32 v5, 0xffff0000, v5
	v_and_b32_e32 v4, 0xffff0000, v4
	v_or_b32_sdwa v3, v5, v3 dst_sel:DWORD dst_unused:UNUSED_PAD src0_sel:DWORD src1_sel:WORD_1
	v_or_b32_sdwa v2, v4, v2 dst_sel:DWORD dst_unused:UNUSED_PAD src0_sel:DWORD src1_sel:WORD_1
	global_store_dwordx2 v[76:77], v[2:3], off offset:1024
	v_mov_b64_e32 v[2:3], v[236:237]
	v_pk_mov_b32 v[6:7], v[36:37], v[16:17] op_sel:[1,0]
	v_mov_b32_e32 v37, v17
	v_pk_add_f32 v[6:7], v[6:7], v[36:37]
	v_pk_fma_f32 v[8:9], v[24:25], v[24:25], v[10:11] op_sel_hi:[1,1,0]
	v_pk_fma_f32 v[10:11], v[26:27], v[26:27], v[14:15] op_sel_hi:[1,1,0]
	v_pk_add_f32 v[6:7], v[6:7], v[6:7] op_sel:[0,1] op_sel_hi:[1,0]
	v_mov_b32_e32 v9, v46
	v_mov_b32_e32 v11, v47
	v_mov_b32_e32 v7, v15
	v_pk_add_f32 v[8:9], v[8:9], v[10:11]
	v_pk_add_f32 v[6:7], v[12:13], v[6:7]
	s_nop 0
	v_pk_add_f32 v[6:7], v[6:7], v[8:9]
	v_mov_b64_e32 v[4:5], v[238:239]
	v_mov_b32_e32 v9, v4
	v_add_f32_e32 v6, v6, v7
	ds_bpermute_b32 v7, v92, v6
	v_mov_b32_e32 v4, v3
	v_mov_b32_e32 v8, v2
	v_pk_mul_f32 v[0:1], v[8:9], v[0:1]
	s_waitcnt lgkmcnt(0)
	v_add_f32_e32 v10, v6, v7
	v_pk_mul_f32 v[6:7], v[40:41], v[38:39] op_sel_hi:[0,1]
	v_pk_mul_f32 v[2:3], v[4:5], v[6:7]
	v_and_b32_sdwa v4, v1, v98 dst_sel:DWORD dst_unused:UNUSED_PAD src0_sel:WORD_1 src1_sel:DWORD
	v_and_b32_sdwa v6, v3, v98 dst_sel:DWORD dst_unused:UNUSED_PAD src0_sel:WORD_1 src1_sel:DWORD
	v_and_b32_sdwa v7, v2, v98 dst_sel:DWORD dst_unused:UNUSED_PAD src0_sel:WORD_1 src1_sel:DWORD
	v_and_b32_sdwa v5, v0, v98 dst_sel:DWORD dst_unused:UNUSED_PAD src0_sel:WORD_1 src1_sel:DWORD
	v_add3_u32 v3, v3, v6, s1
	v_add3_u32 v2, v2, v7, s1
	v_add3_u32 v0, v0, v5, s1
	v_add3_u32 v1, v1, v4, s1
	v_and_b32_e32 v3, 0xffff0000, v3
	v_and_b32_e32 v2, 0xffff0000, v2
	v_or_b32_sdwa v1, v3, v1 dst_sel:DWORD dst_unused:UNUSED_PAD src0_sel:DWORD src1_sel:WORD_1
	v_or_b32_sdwa v0, v2, v0 dst_sel:DWORD dst_unused:UNUSED_PAD src0_sel:DWORD src1_sel:WORD_1
	global_store_dwordx2 v[76:77], v[0:1], off offset:1536
	v_mov_b64_e32 v[0:1], v[224:225]
	ds_bpermute_b32 v4, v93, v10
	s_waitcnt lgkmcnt(0)
	v_add_f32_e32 v4, v10, v4
	ds_bpermute_b32 v5, v94, v4
	s_waitcnt lgkmcnt(0)
	v_add_f32_e32 v4, v4, v5
	ds_bpermute_b32 v5, v95, v4
	s_waitcnt lgkmcnt(0)
	v_add_f32_e32 v4, v4, v5
	ds_bpermute_b32 v5, v96, v4
	s_waitcnt lgkmcnt(0)
	v_add_f32_e32 v4, v4, v5
	ds_bpermute_b32 v5, v97, v4
	s_waitcnt lgkmcnt(0)
	v_add_f32_e32 v4, v4, v5
	v_fmamk_f32 v4, v4, 0x3a800000, v69
	v_rsq_f32_e32 v4, v4
	v_mov_b64_e32 v[2:3], v[226:227]
	v_mov_b32_e32 v11, v2
	v_pk_mul_f32 v[8:9], v[4:5], v[34:35] op_sel_hi:[0,1]
	v_mov_b32_e32 v2, v1
	v_pk_mul_f32 v[6:7], v[4:5], v[18:19] op_sel_hi:[0,1]
	v_mov_b32_e32 v10, v0
	v_pk_mul_f32 v[2:3], v[2:3], v[8:9]
	v_pk_mul_f32 v[0:1], v[10:11], v[6:7]
	v_and_b32_sdwa v7, v3, v98 dst_sel:DWORD dst_unused:UNUSED_PAD src0_sel:WORD_1 src1_sel:DWORD
	v_and_b32_sdwa v8, v2, v98 dst_sel:DWORD dst_unused:UNUSED_PAD src0_sel:WORD_1 src1_sel:DWORD
	v_and_b32_sdwa v5, v1, v98 dst_sel:DWORD dst_unused:UNUSED_PAD src0_sel:WORD_1 src1_sel:DWORD
	v_and_b32_sdwa v6, v0, v98 dst_sel:DWORD dst_unused:UNUSED_PAD src0_sel:WORD_1 src1_sel:DWORD
	v_add3_u32 v3, v3, v7, s1
	v_add3_u32 v2, v2, v8, s1
	v_add3_u32 v0, v0, v6, s1
	v_add3_u32 v1, v1, v5, s1
	s_cbranch_execz .Ldry_p0b_real
; __device__ __forceinline__ unsigned pk2(float lo, float hi) { return f2bf(lo) | (f2bf(hi) << 16); }
; __global__ void __launch_bounds__(512, 2) mk_fwd(Args args) {
;     ...
;             for (int q = 0; q < 4; ++q) {
;                 const float rstd = __builtin_amdgcn_rsqf(s2[q] * (1.f / 1024.f) + RMS_EPS);
;                 u32x2* o8 = (u32x2*)(Hn + (size_t)(m4 + q) * 1024) + lane;
; #pragma unroll
;                 for (int j = 0; j < 4; ++j) { const f32x4 gg = *((const f32x4*)norm_g + lane + 64 * j);
;                     o8[64 * j] = (u32x2){pk2(v[q][j][0] * rstd * gg[0], v[q][j][1] * rstd * gg[1]), pk2(v[q][j][2] * rstd * gg[2], v[q][j][3] * rstd * gg[3])}; }
;             }
.Ldry_p0b_c7:
	v_and_b32_e32 v3, 0xffff0000, v3
	v_and_b32_e32 v2, 0xffff0000, v2
	v_or_b32_sdwa v1, v3, v1 dst_sel:DWORD dst_unused:UNUSED_PAD src0_sel:DWORD src1_sel:WORD_1
	v_or_b32_sdwa v0, v2, v0 dst_sel:DWORD dst_unused:UNUSED_PAD src0_sel:DWORD src1_sel:WORD_1
	global_store_dwordx2 v[76:77], v[0:1], off offset:2048
	v_mov_b64_e32 v[0:1], v[228:229]
	v_mov_b32_e32 v7, v30
	v_mov_b32_e32 v30, v29
	v_mov_b32_e32 v6, v28
	v_pk_mul_f32 v[8:9], v[4:5], v[30:31] op_sel_hi:[0,1]
	v_pk_mul_f32 v[6:7], v[4:5], v[6:7] op_sel_hi:[0,1]
	v_mov_b64_e32 v[2:3], v[230:231]
	v_mov_b32_e32 v11, v2
	v_mov_b32_e32 v2, v1
	v_mov_b32_e32 v10, v0
	v_pk_mul_f32 v[2:3], v[2:3], v[8:9]
	v_pk_mul_f32 v[0:1], v[10:11], v[6:7]
	v_and_b32_sdwa v7, v3, v98 dst_sel:DWORD dst_unused:UNUSED_PAD src0_sel:WORD_1 src1_sel:DWORD
	v_and_b32_sdwa v8, v2, v98 dst_sel:DWORD dst_unused:UNUSED_PAD src0_sel:WORD_1 src1_sel:DWORD
	v_and_b32_sdwa v5, v1, v98 dst_sel:DWORD dst_unused:UNUSED_PAD src0_sel:WORD_1 src1_sel:DWORD
	v_and_b32_sdwa v6, v0, v98 dst_sel:DWORD dst_unused:UNUSED_PAD src0_sel:WORD_1 src1_sel:DWORD
	v_add3_u32 v3, v3, v7, s1
	v_add3_u32 v2, v2, v8, s1
	v_add3_u32 v0, v0, v6, s1
	v_add3_u32 v1, v1, v5, s1
	v_and_b32_e32 v3, 0xffff0000, v3
	v_and_b32_e32 v2, 0xffff0000, v2
	v_or_b32_sdwa v1, v3, v1 dst_sel:DWORD dst_unused:UNUSED_PAD src0_sel:DWORD src1_sel:WORD_1
	v_or_b32_sdwa v0, v2, v0 dst_sel:DWORD dst_unused:UNUSED_PAD src0_sel:DWORD src1_sel:WORD_1
	global_store_dwordx2 v[76:77], v[0:1], off offset:2560
	v_mov_b64_e32 v[0:1], v[232:233]
	v_mov_b32_e32 v7, v26
	v_mov_b32_e32 v26, v25
	v_mov_b32_e32 v6, v24
	v_pk_mul_f32 v[8:9], v[4:5], v[26:27] op_sel_hi:[0,1]
	v_pk_mul_f32 v[6:7], v[4:5], v[6:7] op_sel_hi:[0,1]
	v_mov_b64_e32 v[2:3], v[234:235]
	v_mov_b32_e32 v11, v2
	v_mov_b32_e32 v2, v1
	v_mov_b32_e32 v10, v0
	v_pk_mul_f32 v[2:3], v[2:3], v[8:9]
	v_pk_mul_f32 v[0:1], v[10:11], v[6:7]
	v_and_b32_sdwa v7, v3, v98 dst_sel:DWORD dst_unused:UNUSED_PAD src0_sel:WORD_1 src1_sel:DWORD
	v_and_b32_sdwa v8, v2, v98 dst_sel:DWORD dst_unused:UNUSED_PAD src0_sel:WORD_1 src1_sel:DWORD
	v_and_b32_sdwa v5, v1, v98 dst_sel:DWORD dst_unused:UNUSED_PAD src0_sel:WORD_1 src1_sel:DWORD
	v_and_b32_sdwa v6, v0, v98 dst_sel:DWORD dst_unused:UNUSED_PAD src0_sel:WORD_1 src1_sel:DWORD
	v_add3_u32 v3, v3, v7, s1
	v_add3_u32 v2, v2, v8, s1
	v_add3_u32 v0, v0, v6, s1
	v_add3_u32 v1, v1, v5, s1
	v_and_b32_e32 v3, 0xffff0000, v3
	v_and_b32_e32 v2, 0xffff0000, v2
	v_or_b32_sdwa v1, v3, v1 dst_sel:DWORD dst_unused:UNUSED_PAD src0_sel:DWORD src1_sel:WORD_1
	v_or_b32_sdwa v0, v2, v0 dst_sel:DWORD dst_unused:UNUSED_PAD src0_sel:DWORD src1_sel:WORD_1
	global_store_dwordx2 v[76:77], v[0:1], off offset:3072
	v_mov_b64_e32 v[0:1], v[236:237]
	v_mov_b32_e32 v6, v20
	v_mov_b32_e32 v7, v22
	v_mov_b32_e32 v22, v21
	v_pk_mul_f32 v[6:7], v[4:5], v[6:7] op_sel_hi:[0,1]
	v_pk_mul_f32 v[4:5], v[4:5], v[22:23] op_sel_hi:[0,1]
	v_mov_b64_e32 v[2:3], v[238:239]
	v_mov_b32_e32 v9, v2
	v_mov_b32_e32 v2, v1
	v_mov_b32_e32 v8, v0
	v_pk_mul_f32 v[2:3], v[2:3], v[4:5]
	v_pk_mul_f32 v[0:1], v[8:9], v[6:7]
	v_and_b32_sdwa v6, v3, v98 dst_sel:DWORD dst_unused:UNUSED_PAD src0_sel:WORD_1 src1_sel:DWORD
	v_and_b32_sdwa v7, v2, v98 dst_sel:DWORD dst_unused:UNUSED_PAD src0_sel:WORD_1 src1_sel:DWORD
	v_and_b32_sdwa v4, v1, v98 dst_sel:DWORD dst_unused:UNUSED_PAD src0_sel:WORD_1 src1_sel:DWORD
	v_and_b32_sdwa v5, v0, v98 dst_sel:DWORD dst_unused:UNUSED_PAD src0_sel:WORD_1 src1_sel:DWORD
	v_add3_u32 v3, v3, v6, s1
	v_add3_u32 v2, v2, v7, s1
	v_add3_u32 v0, v0, v5, s1
	v_add3_u32 v1, v1, v4, s1
	v_and_b32_e32 v3, 0xffff0000, v3
	v_and_b32_e32 v2, 0xffff0000, v2
	v_or_b32_sdwa v1, v3, v1 dst_sel:DWORD dst_unused:UNUSED_PAD src0_sel:DWORD src1_sel:WORD_1
	v_or_b32_sdwa v0, v2, v0 dst_sel:DWORD dst_unused:UNUSED_PAD src0_sel:DWORD src1_sel:WORD_1
	global_store_dwordx2 v[76:77], v[0:1], off offset:3584
	s_cbranch_execz .Ldry_p0b_real
	s_andn2_b64 exec, exec, s[16:17]
	s_cbranch_execnz .LBB0_12

; __device__ __forceinline__ float bf2f(unsigned u) { return __uint_as_float(u << 16); }
; template <bool FULL>
; __device__ __forceinline__ void hg_load(HgRegs& R, size_t m0, int h, const float* G, const bf16_t* HQ, const bf16_t* HI) {
;     const int tid = threadIdx.x, k = tid & 127, part = tid >> 7;
;     const size_t base = (m0 + 16 * part) * 1024 + h * 128 + k;
; #pragma unroll
;     for (int i = 0; i < 16; ++i) R.gv[i] = bf2f(((const bf16_t*)G)[base + (size_t)i * 1024]);
; #pragma unroll
;     for (int i = 0; i < 16; ++i) R.vv[i] = HI[base + (size_t)i * 1024];
;     if (FULL) {
; #pragma unroll
;         for (int i = 0; i < 16; ++i) R.qv[i] = HQ[base + (size_t)i * 1024];
;     }
; __device__ __forceinline__ void hg_unit_c(LAS unsigned char* lds, int unit, const float* G, bf16_t* HQ, const bf16_t* HI, const float* ST, const float* ng) {
;     ...
;         const float* U = ST + (size_t)unit * 16384;
; #pragma unroll
;         for (int i = 0; i < 8; ++i)
; #pragma unroll
;             for (int rg = 0; rg < 4; ++rg) S[i][rg] = U[(16 * i + 4 * g + rg) * 128 + 16 * w + r];
.LBB0_430:
	s_lshl_b32 s3, s60, 1
	s_lshl_b32 s36, s58, 11
	s_ashr_i32 s79, s78, 31
	s_and_b32 s45, s58, 0x1f00
	s_and_b32 s3, s3, 0x700
	s_and_b32 s44, s36, 0xf80000
	s_lshl_b64 s[38:39], s[78:79], 16
	s_add_u32 s38, s52, s38
	s_addc_u32 s39, s53, s39
	v_lshl_add_u64 v[10:11], s[38:39], 0, v[40:41]
	v_add_co_u32_e32 v12, vcc, s80, v10
	s_ashr_i32 s40, s78, 8
	s_nop 0
	v_addc_co_u32_e32 v13, vcc, 0, v11, vcc
	v_add_co_u32_e32 v14, vcc, s81, v10
	s_ashr_i32 s41, s40, 31
	s_nop 0
	v_addc_co_u32_e32 v15, vcc, 0, v11, vcc
	v_add_co_u32_e32 v32, vcc, s82, v10
	s_lshl_b32 s36, s78, 8
	s_nop 0
	v_addc_co_u32_e32 v33, vcc, 0, v11, vcc
	s_lshl_b64 s[48:49], s[40:41], 13
	s_and_b32 s36, s36, 0x1f00
	v_add_co_u32_e32 v34, vcc, s83, v10
	s_or_b32 s36, s48, s36
	global_load_dword v17, v105, s[38:39]
	global_load_dword v18, v106, s[38:39]
	global_load_dword v19, v107, s[38:39]
	global_load_dword v24, v108, s[38:39]
	global_load_dword v25, v109, s[38:39]
	global_load_dword v26, v110, s[38:39]
	global_load_dword v27, v111, s[38:39]
	global_load_dword v20, v112, s[38:39]
	global_load_dword v21, v113, s[38:39]
	global_load_dword v22, v114, s[38:39]
	global_load_dword v23, v115, s[38:39]
	global_load_dword v28, v116, s[38:39]
	global_load_dword v29, v117, s[38:39]
	global_load_dword v30, v118, s[38:39]
	global_load_dword v31, v119, s[38:39]
	global_load_dword v0, v[12:13], off
	global_load_dword v1, v120, s[38:39]
	global_load_dword v3, v121, s[38:39]
	global_load_dword v4, v[14:15], off
	global_load_dword v5, v122, s[38:39]
	global_load_dword v7, v123, s[38:39]
	global_load_dword v8, v[32:33], off
	global_load_dword v6, v[14:15], off offset:1024
	global_load_dword v2, v[12:13], off offset:1024
	v_addc_co_u32_e32 v35, vcc, 0, v11, vcc
	global_load_dword v9, v124, s[38:39]
	global_load_dword v11, v125, s[38:39]
	global_load_dword v12, v[34:35], off
	global_load_dword v13, v126, s[38:39]
	global_load_dword v15, v127, s[38:39]
	global_load_dword v14, v[34:35], off offset:1024
	global_load_dword v10, v[32:33], off offset:1024
	v_mov_b32_e32 v33, s49
	v_or_b32_e32 v32, s36, v46
	s_lshl_b32 s36, s78, 2
	v_lshlrev_b64 v[32:33], 10, v[32:33]
	s_and_b32 s36, s36, 0x380
	v_or_b32_e32 v16, s36, v32
	v_or_b32_e32 v32, v16, v42
	v_lshlrev_b64 v[32:33], 1, v[32:33]
	v_lshl_add_u64 v[34:35], s[64:65], 0, v[32:33]
	v_add_co_u32_e32 v36, vcc, s1, v34
	s_lshl_b32 s36, s36, 2
	s_nop 0
	v_addc_co_u32_e32 v37, vcc, 0, v35, vcc
	v_add_co_u32_e32 v38, vcc, s85, v34
	s_nop 1
	v_addc_co_u32_e32 v39, vcc, 0, v35, vcc
	v_add_co_u32_e32 v56, vcc, s87, v34
	s_nop 1
	v_addc_co_u32_e32 v57, vcc, 0, v35, vcc
	v_add_co_u32_e32 v58, vcc, s89, v34
	s_nop 1
	v_addc_co_u32_e32 v59, vcc, 0, v35, vcc
	global_load_ushort v64, v[34:35], off offset:2048
	global_load_ushort v66, v[36:37], off offset:2048
	global_load_ushort v70, v[38:39], off offset:2048
	global_load_ushort v74, v[56:57], off offset:2048
	global_load_ushort v78, v[58:59], off offset:2048
	global_load_ushort v73, v[58:59], off
	global_load_ushort v43, v[34:35], off
	v_add_co_u32_e32 v36, vcc, s84, v34
	s_nop 0
	s_nop 0
	v_addc_co_u32_e32 v37, vcc, 0, v35, vcc
	v_add_co_u32_e32 v38, vcc, s86, v34
	s_nop 0
	s_nop 0
	v_addc_co_u32_e32 v39, vcc, 0, v35, vcc
	v_add_co_u32_e32 v34, vcc, s88, v34
	s_nop 0
	s_nop 0
	v_addc_co_u32_e32 v35, vcc, 0, v35, vcc
	global_load_ushort v45, v[36:37], off offset:-4096
	global_load_ushort v68, v[36:37], off offset:2048
	global_load_ushort v65, v[38:39], off offset:-4096
	global_load_ushort v72, v[38:39], off offset:2048
	global_load_ushort v69, v[34:35], off offset:-4096
	global_load_ushort v71, v[34:35], off
	global_load_ushort v67, v[38:39], off
	global_load_ushort v47, v[36:37], off
	global_load_ushort v76, v[34:35], off offset:2048
	v_lshl_add_u64 v[34:35], s[42:43], 0, v[32:33]
	v_add_co_u32_e32 v36, vcc, s1, v34
	v_lshl_add_u64 v[32:33], s[46:47], 0, v[32:33]
	s_nop 0
	v_addc_co_u32_e32 v37, vcc, 0, v35, vcc
	v_add_co_u32_e32 v38, vcc, s84, v34
	s_nop 0
	s_nop 0
	v_addc_co_u32_e32 v39, vcc, 0, v35, vcc
	v_add_co_u32_e32 v56, vcc, s85, v34
	s_nop 0
	s_nop 0
	v_addc_co_u32_e32 v57, vcc, 0, v35, vcc
	v_add_co_u32_e32 v58, vcc, s86, v34
	s_nop 0
	s_nop 0
	v_addc_co_u32_e32 v59, vcc, 0, v35, vcc
	v_add_co_u32_e32 v60, vcc, s87, v34
	s_nop 0
	s_nop 0
	v_addc_co_u32_e32 v61, vcc, 0, v35, vcc
	v_add_co_u32_e32 v62, vcc, s88, v34
	s_nop 0
	s_nop 0
	v_addc_co_u32_e32 v63, vcc, 0, v35, vcc
	global_load_ushort v135, v[38:39], off offset:-4096
	global_load_ushort v136, v[38:39], off
	global_load_ushort v137, v[38:39], off offset:2048
	global_load_ushort v138, v[58:59], off offset:-4096
	global_load_ushort v143, v[58:59], off
	global_load_ushort v144, v[58:59], off offset:2048
	global_load_ushort v145, v[62:63], off offset:-4096
	global_load_ushort v146, v[62:63], off
	v_add_co_u32_e32 v38, vcc, s89, v34
	s_nop 0
	s_nop 0
	v_addc_co_u32_e32 v39, vcc, 0, v35, vcc
	global_load_ushort v139, v[34:35], off
	global_load_ushort v140, v[34:35], off offset:2048
	global_load_ushort v141, v[36:37], off offset:2048
	global_load_ushort v142, v[56:57], off offset:2048
	global_load_ushort v147, v[60:61], off offset:2048
	global_load_ushort v148, v[38:39], off
	global_load_ushort v149, v[38:39], off offset:2048
	global_load_ushort v150, v[32:33], off
	v_add_co_u32_e32 v34, vcc, s1, v32
	s_nop 0
	s_nop 0
	v_addc_co_u32_e32 v35, vcc, 0, v33, vcc
	v_add_co_u32_e32 v36, vcc, s84, v32
	s_nop 0
	s_nop 0
	v_addc_co_u32_e32 v37, vcc, 0, v33, vcc
	v_add_co_u32_e32 v38, vcc, s85, v32
	s_nop 0
	s_nop 0
	v_addc_co_u32_e32 v39, vcc, 0, v33, vcc
	v_add_co_u32_e32 v56, vcc, s86, v32
	s_nop 0
	s_nop 0
	v_addc_co_u32_e32 v57, vcc, 0, v33, vcc
	v_add_co_u32_e32 v58, vcc, s87, v32
	s_nop 0
	s_nop 0
	v_addc_co_u32_e32 v59, vcc, 0, v33, vcc
	v_add_co_u32_e32 v60, vcc, s88, v32
	s_nop 0
	s_nop 0
	v_addc_co_u32_e32 v61, vcc, 0, v33, vcc
	global_load_ushort v151, v[62:63], off offset:2048
	global_load_ushort v152, v[36:37], off offset:-4096
	global_load_ushort v153, v[36:37], off
	global_load_ushort v154, v[36:37], off offset:2048
	global_load_ushort v155, v[56:57], off offset:-4096
	global_load_ushort v159, v[56:57], off
	global_load_ushort v160, v[56:57], off offset:2048
	global_load_ushort v161, v[60:61], off offset:-4096
	global_load_ushort v162, v[60:61], off
	global_load_ushort v163, v[60:61], off offset:2048
	v_add_co_u32_e32 v36, vcc, s89, v32
	v_lshl_add_u64 v[56:57], v[48:49], 0, s[36:37]
	s_nop 0
	v_addc_co_u32_e32 v37, vcc, 0, v33, vcc
	global_load_dword v16, v40, s[38:39]
	global_load_ushort v156, v[32:33], off offset:2048
	global_load_ushort v157, v[34:35], off offset:2048
	global_load_ushort v158, v[38:39], off offset:2048
	global_load_ushort v164, v[58:59], off offset:2048
	global_load_ushort v165, v[36:37], off
	global_load_ushort v166, v[36:37], off offset:2048
	v_or_b32_e32 v32, s48, v44
	v_mov_b32_e32 v33, s49
	v_or_b32_e32 v32, s45, v32
	s_lshl_b64 s[38:39], s[40:41], 24
	v_lshlrev_b64 v[32:33], 11, v[32:33]
	s_or_b32 s36, s38, s44
	v_or_b32_e32 v32, s3, v32
	s_or_b32 s38, s36, s3
	s_waitcnt vmcnt(33)
; __device__ __forceinline__ float bf2f(unsigned u) { return __uint_as_float(u << 16); }
; template <bool FULL>
; __device__ __forceinline__ void hg_load(HgRegs& R, size_t m0, int h, const float* G, const bf16_t* HQ, const bf16_t* HI) {
;     ...
;     for (int i = 0; i < 16; ++i) R.gv[i] = bf2f(((const bf16_t*)G)[base + (size_t)i * 1024]);
; #pragma unroll
;     for (int i = 0; i < 16; ++i) R.vv[i] = HI[base + (size_t)i * 1024];
;     if (FULL) {
; #pragma unroll
;         for (int i = 0; i < 16; ++i) R.qv[i] = HQ[base + (size_t)i * 1024];
;     }
	v_lshlrev_b32_e32 v76, 16, v76
	v_lshlrev_b32_e32 v43, 16, v43
	v_lshlrev_b32_e32 v64, 16, v64
	v_lshlrev_b32_e32 v45, 16, v45
	v_lshlrev_b32_e32 v66, 16, v66
	v_lshlrev_b32_e32 v47, 16, v47
	v_lshlrev_b32_e32 v68, 16, v68
	v_lshlrev_b32_e32 v65, 16, v65
	v_lshlrev_b32_e32 v70, 16, v70
	v_lshlrev_b32_e32 v67, 16, v67
	v_lshlrev_b32_e32 v72, 16, v72
	v_lshlrev_b32_e32 v69, 16, v69
	v_lshlrev_b32_e32 v74, 16, v74
	v_lshlrev_b32_e32 v71, 16, v71
	v_lshlrev_b32_e32 v73, 16, v73
	v_lshlrev_b32_e32 v78, 16, v78
	v_lshl_add_u64 v[58:59], v[50:51], 0, v[32:33]
	v_lshl_add_u64 v[60:61], v[52:53], 0, s[38:39]
	v_lshl_add_u64 v[62:63], v[54:55], 0, s[38:39]
	s_mov_b64 s[38:39], 0
	s_branch .LBB0_432
